# P5 rope epilogue: prefetch next row-block cos/sin tables into spare regs, counted waits instead of full drains
# baseline (speedup 1.0000x reference)
.LBB0_259:
	s_or_b32 s16, s4, s48
	s_ashr_i32 s17, s16, 31
	s_and_b64 vcc, exec, s[40:41]
	v_lshlrev_b32_e32 v158, 1, v138
	s_cbranch_vccz .LBB0_263
	v_and_b32_e32 v159, 0x7cf, v173
	v_cmp_gt_i32_e32 vcc, s94, v173
	v_mov_b32_e32 v165, v1
	v_lshl_add_u64 v[162:163], s[16:17], 1, v[162:163]
	v_cndmask_b32_e32 v159, v167, v159, vcc
	v_lshlrev_b32_e32 v164, 7, v159
	v_lshl_add_u64 v[178:179], v[142:143], 0, v[164:165]
	global_load_dwordx4 v[174:177], v[178:179], off
	s_nop 0
	global_load_dwordx4 v[178:181], v[178:179], off offset:16
	v_lshl_add_u64 v[164:165], v[140:141], 0, v[164:165]
	global_load_dwordx4 v[182:185], v[164:165], off
	global_load_dwordx4 v[186:189], v[164:165], off offset:16
	v_or_b32_e32 v240, s20, v168
	v_cmp_gt_i32_e32 vcc, s94, v240
	v_and_b32_e32 v240, 0x7ff, v240
	v_mov_b32_e32 v241, 0
	v_cndmask_b32_e32 v240, v169, v240, vcc
	v_lshlrev_b32_e32 v240, 7, v240
	v_lshl_add_u64 v[242:243], v[142:143], 0, v[240:241]
	v_lshl_add_u64 v[244:245], v[140:141], 0, v[240:241]
	global_load_dwordx4 v[224:227], v[242:243], off
	global_load_dwordx4 v[228:231], v[242:243], off offset:16
	global_load_dwordx4 v[232:235], v[244:245], off
	global_load_dwordx4 v[236:239], v[244:245], off offset:16
	v_mov_b32_e32 v159, v1
	v_lshl_add_u64 v[190:191], v[162:163], 0, v[158:159]
	v_cmp_ne_u64_e32 vcc, 0, v[160:161]
	s_waitcnt vmcnt(4)
	v_pk_mul_f32 v[162:163], v[120:121], v[176:177]
	v_pk_mul_f32 v[164:165], v[118:119], v[174:175]
	v_pk_mul_f32 v[192:193], v[116:117], v[180:181]
	v_pk_mul_f32 v[206:207], v[114:115], v[178:179]
	v_pk_mul_f32 v[176:177], v[128:129], v[176:177]
	v_pk_mul_f32 v[174:175], v[126:127], v[174:175]
	v_pk_mul_f32 v[180:181], v[124:125], v[180:181]
	v_pk_mul_f32 v[178:179], v[122:123], v[178:179]
	v_pk_fma_f32 v[128:129], v[128:129], v[184:185], v[162:163] neg_lo:[0,0,1] neg_hi:[0,0,1]
	v_pk_fma_f32 v[126:127], v[126:127], v[182:183], v[164:165] neg_lo:[0,0,1] neg_hi:[0,0,1]
	v_pk_fma_f32 v[124:125], v[124:125], v[188:189], v[192:193] neg_lo:[0,0,1] neg_hi:[0,0,1]
	v_pk_fma_f32 v[122:123], v[122:123], v[186:187], v[206:207] neg_lo:[0,0,1] neg_hi:[0,0,1]
	v_pk_fma_f32 v[120:121], v[120:121], v[184:185], v[176:177]
	v_pk_fma_f32 v[118:119], v[118:119], v[182:183], v[174:175]
	v_pk_fma_f32 v[116:117], v[116:117], v[188:189], v[180:181]
	v_pk_fma_f32 v[114:115], v[114:115], v[186:187], v[178:179]
	v_cvt_pk_bf16_f32 v162, v126, v127
	v_cvt_pk_bf16_f32 v163, v128, v129
	v_cvt_pk_bf16_f32 v164, v122, v123
	v_cvt_pk_bf16_f32 v165, v124, v125
	v_cvt_pk_bf16_f32 v174, v118, v119
	v_cvt_pk_bf16_f32 v175, v120, v121
	s_nop 0
	v_cvt_pk_bf16_f32 v176, v114, v115
	v_cvt_pk_bf16_f32 v177, v116, v117
	global_store_dwordx4 v[190:191], v[162:165], off
	global_store_dwordx4 v[190:191], v[174:177], off offset:64
	s_and_saveexec_b64 s[0:1], vcc
	s_cbranch_execz .LBB0_262
	v_lshl_add_u64 v[160:161], s[16:17], 2, v[160:161]
	v_lshlrev_b32_e32 v162, 2, v138
	v_mov_b32_e32 v163, v1
	v_lshl_add_u64 v[160:161], v[160:161], 0, v[162:163]
	global_store_dwordx4 v[160:161], v[126:129], off offset:-4096
	global_store_dwordx4 v[160:161], v[122:125], off offset:-4080
	global_store_dwordx4 v[160:161], v[118:121], off offset:-3968
	global_store_dwordx4 v[160:161], v[114:117], off offset:-3952

.LBB0_275:
	s_and_b64 vcc, exec, s[4:5]
	s_cbranch_vccz .LBB0_279
	v_and_b32_e32 v118, 0x7df, v122
	v_cmp_gt_i32_e32 vcc, s94, v122
	v_mov_b32_e32 v127, v1
	v_lshl_add_u64 v[116:117], s[16:17], 1, v[116:117]
	v_cndmask_b32_e32 v118, v169, v118, vcc
	v_lshlrev_b32_e32 v126, 7, v118
	v_lshl_add_u64 v[122:123], v[142:143], 0, v[126:127]
	s_nop 0
	v_lshl_add_u64 v[160:161], v[140:141], 0, v[126:127]
	s_nop 0
	v_or_b32_e32 v240, s20, v170
	v_cmp_gt_i32_e32 vcc, s94, v240
	v_and_b32_e32 v240, 0x7ff, v240
	v_mov_b32_e32 v241, 0
	v_cndmask_b32_e32 v240, v167, v240, vcc
	v_lshlrev_b32_e32 v240, 7, v240
	v_lshl_add_u64 v[242:243], v[142:143], 0, v[240:241]
	v_lshl_add_u64 v[244:245], v[140:141], 0, v[240:241]
	global_load_dwordx4 v[208:211], v[242:243], off
	global_load_dwordx4 v[212:215], v[242:243], off offset:16
	global_load_dwordx4 v[216:219], v[244:245], off
	global_load_dwordx4 v[220:223], v[244:245], off offset:16
	v_mov_b32_e32 v159, v1
	v_lshl_add_u64 v[164:165], v[116:117], 0, v[158:159]
	v_cmp_ne_u64_e32 vcc, 0, v[114:115]
	s_waitcnt vmcnt(6)
	v_pk_mul_f32 v[116:117], v[104:105], v[226:227]
	v_pk_mul_f32 v[174:175], v[102:103], v[224:225]
	v_pk_mul_f32 v[176:177], v[100:101], v[230:231]
	v_pk_mul_f32 v[178:179], v[98:99], v[228:229]
	v_pk_mul_f32 v[120:121], v[112:113], v[226:227]
	v_pk_mul_f32 v[118:119], v[110:111], v[224:225]
	v_pk_mul_f32 v[124:125], v[108:109], v[230:231]
	v_pk_mul_f32 v[122:123], v[106:107], v[228:229]
	v_pk_fma_f32 v[112:113], v[112:113], v[234:235], v[116:117] neg_lo:[0,0,1] neg_hi:[0,0,1]
	v_pk_fma_f32 v[110:111], v[110:111], v[232:233], v[174:175] neg_lo:[0,0,1] neg_hi:[0,0,1]
	v_pk_fma_f32 v[108:109], v[108:109], v[238:239], v[176:177] neg_lo:[0,0,1] neg_hi:[0,0,1]
	v_pk_fma_f32 v[106:107], v[106:107], v[236:237], v[178:179] neg_lo:[0,0,1] neg_hi:[0,0,1]
	v_pk_fma_f32 v[104:105], v[104:105], v[234:235], v[120:121]
	v_pk_fma_f32 v[102:103], v[102:103], v[232:233], v[118:119]
	v_pk_fma_f32 v[100:101], v[100:101], v[238:239], v[124:125]
	v_pk_fma_f32 v[98:99], v[98:99], v[236:237], v[122:123]
	v_cvt_pk_bf16_f32 v116, v110, v111
	v_cvt_pk_bf16_f32 v117, v112, v113
	v_cvt_pk_bf16_f32 v118, v106, v107
	v_cvt_pk_bf16_f32 v119, v108, v109
	v_cvt_pk_bf16_f32 v120, v102, v103
	v_cvt_pk_bf16_f32 v121, v104, v105
	s_nop 0
	v_cvt_pk_bf16_f32 v122, v98, v99
	v_cvt_pk_bf16_f32 v123, v100, v101
	global_store_dwordx4 v[164:165], v[116:119], off
	global_store_dwordx4 v[164:165], v[120:123], off offset:64
	s_and_saveexec_b64 s[0:1], vcc
	s_cbranch_execz .LBB0_278
	v_lshl_add_u64 v[114:115], s[16:17], 2, v[114:115]
	v_lshlrev_b32_e32 v116, 2, v138
	v_mov_b32_e32 v117, v1
	v_lshl_add_u64 v[114:115], v[114:115], 0, v[116:117]
	global_store_dwordx4 v[114:115], v[110:113], off offset:-4096
	global_store_dwordx4 v[114:115], v[106:109], off offset:-4080
	global_store_dwordx4 v[114:115], v[102:105], off offset:-3968
	global_store_dwordx4 v[114:115], v[98:101], off offset:-3952

.LBB0_291:
	s_and_b64 vcc, exec, s[4:5]
	s_cbranch_vccz .LBB0_295
	v_and_b32_e32 v102, 0x7ef, v106
	v_cmp_gt_i32_e32 vcc, s94, v106
	v_mov_b32_e32 v111, v1
	v_lshl_add_u64 v[100:101], s[16:17], 1, v[100:101]
	v_cndmask_b32_e32 v102, v167, v102, vcc
	v_lshlrev_b32_e32 v110, 7, v102
	v_lshl_add_u64 v[106:107], v[142:143], 0, v[110:111]
	s_nop 0
	v_lshl_add_u64 v[114:115], v[140:141], 0, v[110:111]
	s_nop 0
	v_or_b32_e32 v240, s20, v171
	v_cmp_gt_i32_e32 vcc, s94, v240
	v_and_b32_e32 v240, 0x7ff, v240
	v_mov_b32_e32 v241, 0
	v_cndmask_b32_e32 v240, v169, v240, vcc
	v_lshlrev_b32_e32 v240, 7, v240
	v_lshl_add_u64 v[242:243], v[142:143], 0, v[240:241]
	v_lshl_add_u64 v[244:245], v[140:141], 0, v[240:241]
	global_load_dwordx4 v[224:227], v[242:243], off
	global_load_dwordx4 v[228:231], v[242:243], off offset:16
	global_load_dwordx4 v[232:235], v[244:245], off
	global_load_dwordx4 v[236:239], v[244:245], off offset:16
	v_mov_b32_e32 v159, v1
	v_lshl_add_u64 v[118:119], v[100:101], 0, v[158:159]
	v_cmp_ne_u64_e32 vcc, 0, v[98:99]
	s_waitcnt vmcnt(6)
	v_pk_mul_f32 v[100:101], v[88:89], v[210:211]
	v_pk_mul_f32 v[120:121], v[86:87], v[208:209]
	v_pk_mul_f32 v[122:123], v[84:85], v[214:215]
	v_pk_mul_f32 v[124:125], v[82:83], v[212:213]
	v_pk_mul_f32 v[104:105], v[96:97], v[210:211]
	v_pk_mul_f32 v[102:103], v[94:95], v[208:209]
	v_pk_mul_f32 v[108:109], v[92:93], v[214:215]
	v_pk_mul_f32 v[106:107], v[90:91], v[212:213]
	v_pk_fma_f32 v[96:97], v[96:97], v[218:219], v[100:101] neg_lo:[0,0,1] neg_hi:[0,0,1]
	v_pk_fma_f32 v[94:95], v[94:95], v[216:217], v[120:121] neg_lo:[0,0,1] neg_hi:[0,0,1]
	v_pk_fma_f32 v[92:93], v[92:93], v[222:223], v[122:123] neg_lo:[0,0,1] neg_hi:[0,0,1]
	v_pk_fma_f32 v[90:91], v[90:91], v[220:221], v[124:125] neg_lo:[0,0,1] neg_hi:[0,0,1]
	v_pk_fma_f32 v[88:89], v[88:89], v[218:219], v[104:105]
	v_pk_fma_f32 v[86:87], v[86:87], v[216:217], v[102:103]
	v_pk_fma_f32 v[84:85], v[84:85], v[222:223], v[108:109]
	v_pk_fma_f32 v[82:83], v[82:83], v[220:221], v[106:107]
	v_cvt_pk_bf16_f32 v100, v94, v95
	v_cvt_pk_bf16_f32 v101, v96, v97
	v_cvt_pk_bf16_f32 v102, v90, v91
	v_cvt_pk_bf16_f32 v103, v92, v93
	v_cvt_pk_bf16_f32 v104, v86, v87
	v_cvt_pk_bf16_f32 v105, v88, v89
	s_nop 0
	v_cvt_pk_bf16_f32 v106, v82, v83
	v_cvt_pk_bf16_f32 v107, v84, v85
	global_store_dwordx4 v[118:119], v[100:103], off
	global_store_dwordx4 v[118:119], v[104:107], off offset:64
	s_and_saveexec_b64 s[0:1], vcc
	s_cbranch_execz .LBB0_294
	v_lshl_add_u64 v[98:99], s[16:17], 2, v[98:99]
	v_lshlrev_b32_e32 v100, 2, v138
	v_mov_b32_e32 v101, v1
	v_lshl_add_u64 v[98:99], v[98:99], 0, v[100:101]
	global_store_dwordx4 v[98:99], v[94:97], off offset:-4096
	global_store_dwordx4 v[98:99], v[90:93], off offset:-4080
	global_store_dwordx4 v[98:99], v[86:89], off offset:-3968
	global_store_dwordx4 v[98:99], v[82:85], off offset:-3952

.LBB0_307:
	s_and_b64 vcc, exec, s[4:5]
	s_cbranch_vccz .LBB0_311
	v_and_b32_e32 v86, 0x7ff, v90
	v_cmp_gt_i32_e32 vcc, s94, v90
	v_mov_b32_e32 v95, v1
	v_lshl_add_u64 v[84:85], s[16:17], 1, v[84:85]
	v_cndmask_b32_e32 v86, v169, v86, vcc
	v_lshlrev_b32_e32 v94, 7, v86
	v_lshl_add_u64 v[90:91], v[142:143], 0, v[94:95]
	s_nop 0
	v_lshl_add_u64 v[98:99], v[140:141], 0, v[94:95]
	s_nop 0
	v_or_b32_e32 v240, s20, v139
	v_add_u32_e32 v240, 0x80, v240
	v_cmp_gt_i32_e32 vcc, s94, v240
	v_and_b32_e32 v240, 0x7ff, v240
	v_mov_b32_e32 v241, 0
	v_cndmask_b32_e32 v240, v167, v240, vcc
	v_lshlrev_b32_e32 v240, 7, v240
	v_lshl_add_u64 v[242:243], v[142:143], 0, v[240:241]
	v_lshl_add_u64 v[244:245], v[140:141], 0, v[240:241]
	global_load_dwordx4 v[208:211], v[242:243], off
	global_load_dwordx4 v[212:215], v[242:243], off offset:16
	global_load_dwordx4 v[216:219], v[244:245], off
	global_load_dwordx4 v[220:223], v[244:245], off offset:16
	v_mov_b32_e32 v159, v1
	v_lshl_add_u64 v[102:103], v[84:85], 0, v[158:159]
	v_cmp_ne_u64_e32 vcc, 0, v[82:83]
	s_waitcnt vmcnt(6)
	v_pk_mul_f32 v[84:85], v[72:73], v[226:227]
	v_pk_mul_f32 v[104:105], v[70:71], v[224:225]
	v_pk_mul_f32 v[106:107], v[68:69], v[230:231]
	v_pk_mul_f32 v[108:109], v[66:67], v[228:229]
	v_pk_mul_f32 v[88:89], v[80:81], v[226:227]
	v_pk_mul_f32 v[86:87], v[78:79], v[224:225]
	v_pk_mul_f32 v[92:93], v[76:77], v[230:231]
	v_pk_mul_f32 v[90:91], v[74:75], v[228:229]
	v_pk_fma_f32 v[80:81], v[80:81], v[234:235], v[84:85] neg_lo:[0,0,1] neg_hi:[0,0,1]
	v_pk_fma_f32 v[78:79], v[78:79], v[232:233], v[104:105] neg_lo:[0,0,1] neg_hi:[0,0,1]
	v_pk_fma_f32 v[76:77], v[76:77], v[238:239], v[106:107] neg_lo:[0,0,1] neg_hi:[0,0,1]
	v_pk_fma_f32 v[74:75], v[74:75], v[236:237], v[108:109] neg_lo:[0,0,1] neg_hi:[0,0,1]
	v_pk_fma_f32 v[72:73], v[72:73], v[234:235], v[88:89]
	v_pk_fma_f32 v[70:71], v[70:71], v[232:233], v[86:87]
	v_pk_fma_f32 v[68:69], v[68:69], v[238:239], v[92:93]
	v_pk_fma_f32 v[66:67], v[66:67], v[236:237], v[90:91]
	v_cvt_pk_bf16_f32 v84, v78, v79
	v_cvt_pk_bf16_f32 v85, v80, v81
	v_cvt_pk_bf16_f32 v86, v74, v75
	v_cvt_pk_bf16_f32 v87, v76, v77
	v_cvt_pk_bf16_f32 v88, v70, v71
	v_cvt_pk_bf16_f32 v89, v72, v73
	s_nop 0
	v_cvt_pk_bf16_f32 v90, v66, v67
	v_cvt_pk_bf16_f32 v91, v68, v69
	global_store_dwordx4 v[102:103], v[84:87], off
	global_store_dwordx4 v[102:103], v[88:91], off offset:64
	s_and_saveexec_b64 s[0:1], vcc
	s_cbranch_execz .LBB0_310
	v_lshl_add_u64 v[82:83], s[16:17], 2, v[82:83]
	v_lshlrev_b32_e32 v84, 2, v138
	v_mov_b32_e32 v85, v1
	v_lshl_add_u64 v[82:83], v[82:83], 0, v[84:85]
	global_store_dwordx4 v[82:83], v[78:81], off offset:-4096
	global_store_dwordx4 v[82:83], v[74:77], off offset:-4080
	global_store_dwordx4 v[82:83], v[70:73], off offset:-3968
	global_store_dwordx4 v[82:83], v[66:69], off offset:-3952

.LBB0_323:
	s_and_b64 vcc, exec, s[4:5]
	s_cbranch_vccz .LBB0_327
	v_and_b32_e32 v70, 0x7cf, v74
	v_cmp_gt_i32_e32 vcc, s94, v74
	v_mov_b32_e32 v79, v1
	v_lshl_add_u64 v[68:69], s[16:17], 1, v[68:69]
	v_cndmask_b32_e32 v70, v167, v70, vcc
	v_lshlrev_b32_e32 v78, 7, v70
	v_lshl_add_u64 v[74:75], v[142:143], 0, v[78:79]
	s_nop 0
	v_lshl_add_u64 v[82:83], v[140:141], 0, v[78:79]
	s_nop 0
	v_or_b32_e32 v240, s20, v168
	v_cmp_gt_i32_e32 vcc, s94, v240
	v_and_b32_e32 v240, 0x7ff, v240
	v_mov_b32_e32 v241, 0
	v_cndmask_b32_e32 v240, v169, v240, vcc
	v_lshlrev_b32_e32 v240, 7, v240
	v_lshl_add_u64 v[242:243], v[142:143], 0, v[240:241]
	v_lshl_add_u64 v[244:245], v[140:141], 0, v[240:241]
	global_load_dwordx4 v[224:227], v[242:243], off
	global_load_dwordx4 v[228:231], v[242:243], off offset:16
	global_load_dwordx4 v[232:235], v[244:245], off
	global_load_dwordx4 v[236:239], v[244:245], off offset:16
	v_mov_b32_e32 v159, v1
	v_lshl_add_u64 v[86:87], v[68:69], 0, v[158:159]
	v_cmp_ne_u64_e32 vcc, 0, v[66:67]
	s_waitcnt vmcnt(6)
	v_pk_mul_f32 v[68:69], v[56:57], v[210:211]
	v_pk_mul_f32 v[88:89], v[54:55], v[208:209]
	v_pk_mul_f32 v[90:91], v[52:53], v[214:215]
	v_pk_mul_f32 v[92:93], v[50:51], v[212:213]
	v_pk_mul_f32 v[72:73], v[64:65], v[210:211]
	v_pk_mul_f32 v[70:71], v[62:63], v[208:209]
	v_pk_mul_f32 v[76:77], v[60:61], v[214:215]
	v_pk_mul_f32 v[74:75], v[58:59], v[212:213]
	v_pk_fma_f32 v[64:65], v[64:65], v[218:219], v[68:69] neg_lo:[0,0,1] neg_hi:[0,0,1]
	v_pk_fma_f32 v[62:63], v[62:63], v[216:217], v[88:89] neg_lo:[0,0,1] neg_hi:[0,0,1]
	v_pk_fma_f32 v[60:61], v[60:61], v[222:223], v[90:91] neg_lo:[0,0,1] neg_hi:[0,0,1]
	v_pk_fma_f32 v[58:59], v[58:59], v[220:221], v[92:93] neg_lo:[0,0,1] neg_hi:[0,0,1]
	v_pk_fma_f32 v[56:57], v[56:57], v[218:219], v[72:73]
	v_pk_fma_f32 v[54:55], v[54:55], v[216:217], v[70:71]
	v_pk_fma_f32 v[52:53], v[52:53], v[222:223], v[76:77]
	v_pk_fma_f32 v[50:51], v[50:51], v[220:221], v[74:75]
	v_cvt_pk_bf16_f32 v68, v62, v63
	v_cvt_pk_bf16_f32 v69, v64, v65
	v_cvt_pk_bf16_f32 v70, v58, v59
	v_cvt_pk_bf16_f32 v71, v60, v61
	v_cvt_pk_bf16_f32 v72, v54, v55
	v_cvt_pk_bf16_f32 v73, v56, v57
	s_nop 0
	v_cvt_pk_bf16_f32 v74, v50, v51
	v_cvt_pk_bf16_f32 v75, v52, v53
	global_store_dwordx4 v[86:87], v[68:71], off
	global_store_dwordx4 v[86:87], v[72:75], off offset:64
	s_and_saveexec_b64 s[0:1], vcc
	s_cbranch_execz .LBB0_326
	v_lshl_add_u64 v[66:67], s[16:17], 2, v[66:67]
	v_lshlrev_b32_e32 v68, 2, v138
	v_mov_b32_e32 v69, v1
	v_lshl_add_u64 v[66:67], v[66:67], 0, v[68:69]
	global_store_dwordx4 v[66:67], v[62:65], off offset:-4096
	global_store_dwordx4 v[66:67], v[58:61], off offset:-4080
	global_store_dwordx4 v[66:67], v[54:57], off offset:-3968
	global_store_dwordx4 v[66:67], v[50:53], off offset:-3952

.LBB0_339:
	s_and_b64 vcc, exec, s[4:5]
	s_cbranch_vccz .LBB0_343
	v_and_b32_e32 v54, 0x7df, v58
	v_cmp_gt_i32_e32 vcc, s94, v58
	v_mov_b32_e32 v63, v1
	v_lshl_add_u64 v[52:53], s[16:17], 1, v[52:53]
	v_cndmask_b32_e32 v54, v169, v54, vcc
	v_lshlrev_b32_e32 v62, 7, v54
	v_lshl_add_u64 v[58:59], v[142:143], 0, v[62:63]
	s_nop 0
	v_lshl_add_u64 v[66:67], v[140:141], 0, v[62:63]
	s_nop 0
	v_or_b32_e32 v240, s20, v170
	v_cmp_gt_i32_e32 vcc, s94, v240
	v_and_b32_e32 v240, 0x7ff, v240
	v_mov_b32_e32 v241, 0
	v_cndmask_b32_e32 v240, v167, v240, vcc
	v_lshlrev_b32_e32 v240, 7, v240
	v_lshl_add_u64 v[242:243], v[142:143], 0, v[240:241]
	v_lshl_add_u64 v[244:245], v[140:141], 0, v[240:241]
	global_load_dwordx4 v[208:211], v[242:243], off
	global_load_dwordx4 v[212:215], v[242:243], off offset:16
	global_load_dwordx4 v[216:219], v[244:245], off
	global_load_dwordx4 v[220:223], v[244:245], off offset:16
	v_mov_b32_e32 v159, v1
	v_lshl_add_u64 v[70:71], v[52:53], 0, v[158:159]
	v_cmp_ne_u64_e32 vcc, 0, v[50:51]
	s_waitcnt vmcnt(6)
	v_pk_mul_f32 v[52:53], v[40:41], v[226:227]
	v_pk_mul_f32 v[72:73], v[38:39], v[224:225]
	v_pk_mul_f32 v[74:75], v[36:37], v[230:231]
	v_pk_mul_f32 v[76:77], v[34:35], v[228:229]
	v_pk_mul_f32 v[56:57], v[48:49], v[226:227]
	v_pk_mul_f32 v[54:55], v[46:47], v[224:225]
	v_pk_mul_f32 v[60:61], v[44:45], v[230:231]
	v_pk_mul_f32 v[58:59], v[42:43], v[228:229]
	v_pk_fma_f32 v[48:49], v[48:49], v[234:235], v[52:53] neg_lo:[0,0,1] neg_hi:[0,0,1]
	v_pk_fma_f32 v[46:47], v[46:47], v[232:233], v[72:73] neg_lo:[0,0,1] neg_hi:[0,0,1]
	v_pk_fma_f32 v[44:45], v[44:45], v[238:239], v[74:75] neg_lo:[0,0,1] neg_hi:[0,0,1]
	v_pk_fma_f32 v[42:43], v[42:43], v[236:237], v[76:77] neg_lo:[0,0,1] neg_hi:[0,0,1]
	v_pk_fma_f32 v[40:41], v[40:41], v[234:235], v[56:57]
	v_pk_fma_f32 v[38:39], v[38:39], v[232:233], v[54:55]
	v_pk_fma_f32 v[36:37], v[36:37], v[238:239], v[60:61]
	v_pk_fma_f32 v[34:35], v[34:35], v[236:237], v[58:59]
	v_cvt_pk_bf16_f32 v52, v46, v47
	v_cvt_pk_bf16_f32 v53, v48, v49
	v_cvt_pk_bf16_f32 v54, v42, v43
	v_cvt_pk_bf16_f32 v55, v44, v45
	v_cvt_pk_bf16_f32 v56, v38, v39
	v_cvt_pk_bf16_f32 v57, v40, v41
	s_nop 0
	v_cvt_pk_bf16_f32 v58, v34, v35
	v_cvt_pk_bf16_f32 v59, v36, v37
	global_store_dwordx4 v[70:71], v[52:55], off
	global_store_dwordx4 v[70:71], v[56:59], off offset:64
	s_and_saveexec_b64 s[0:1], vcc
	s_cbranch_execz .LBB0_342
	v_lshl_add_u64 v[50:51], s[16:17], 2, v[50:51]
	v_lshlrev_b32_e32 v52, 2, v138
	v_mov_b32_e32 v53, v1
	v_lshl_add_u64 v[50:51], v[50:51], 0, v[52:53]
	global_store_dwordx4 v[50:51], v[46:49], off offset:-4096
	global_store_dwordx4 v[50:51], v[42:45], off offset:-4080
	global_store_dwordx4 v[50:51], v[38:41], off offset:-3968
	global_store_dwordx4 v[50:51], v[34:37], off offset:-3952

.LBB0_355:
	s_and_b64 vcc, exec, s[4:5]
	s_cbranch_vccz .LBB0_359
	v_and_b32_e32 v38, 0x7ef, v42
	v_cmp_gt_i32_e32 vcc, s94, v42
	v_mov_b32_e32 v47, v1
	v_lshl_add_u64 v[36:37], s[16:17], 1, v[36:37]
	v_cndmask_b32_e32 v38, v167, v38, vcc
	v_lshlrev_b32_e32 v46, 7, v38
	v_lshl_add_u64 v[42:43], v[142:143], 0, v[46:47]
	s_nop 0
	v_lshl_add_u64 v[50:51], v[140:141], 0, v[46:47]
	s_nop 0
	v_or_b32_e32 v240, s20, v171
	v_cmp_gt_i32_e32 vcc, s94, v240
	v_and_b32_e32 v240, 0x7ff, v240
	v_mov_b32_e32 v241, 0
	v_cndmask_b32_e32 v240, v169, v240, vcc
	v_lshlrev_b32_e32 v240, 7, v240
	v_lshl_add_u64 v[242:243], v[142:143], 0, v[240:241]
	v_lshl_add_u64 v[244:245], v[140:141], 0, v[240:241]
	global_load_dwordx4 v[224:227], v[242:243], off
	global_load_dwordx4 v[228:231], v[242:243], off offset:16
	global_load_dwordx4 v[232:235], v[244:245], off
	global_load_dwordx4 v[236:239], v[244:245], off offset:16
	v_mov_b32_e32 v159, v1
	v_lshl_add_u64 v[54:55], v[36:37], 0, v[158:159]
	v_cmp_ne_u64_e32 vcc, 0, v[34:35]
	s_waitcnt vmcnt(6)
	v_pk_mul_f32 v[36:37], v[24:25], v[210:211]
	v_pk_mul_f32 v[56:57], v[22:23], v[208:209]
	v_pk_mul_f32 v[58:59], v[20:21], v[214:215]
	v_pk_mul_f32 v[60:61], v[18:19], v[212:213]
	v_pk_mul_f32 v[40:41], v[32:33], v[210:211]
	v_pk_mul_f32 v[38:39], v[30:31], v[208:209]
	v_pk_mul_f32 v[44:45], v[28:29], v[214:215]
	v_pk_mul_f32 v[42:43], v[26:27], v[212:213]
	v_pk_fma_f32 v[32:33], v[32:33], v[218:219], v[36:37] neg_lo:[0,0,1] neg_hi:[0,0,1]
	v_pk_fma_f32 v[30:31], v[30:31], v[216:217], v[56:57] neg_lo:[0,0,1] neg_hi:[0,0,1]
	v_pk_fma_f32 v[28:29], v[28:29], v[222:223], v[58:59] neg_lo:[0,0,1] neg_hi:[0,0,1]
	v_pk_fma_f32 v[26:27], v[26:27], v[220:221], v[60:61] neg_lo:[0,0,1] neg_hi:[0,0,1]
	v_pk_fma_f32 v[24:25], v[24:25], v[218:219], v[40:41]
	v_pk_fma_f32 v[22:23], v[22:23], v[216:217], v[38:39]
	v_pk_fma_f32 v[20:21], v[20:21], v[222:223], v[44:45]
	v_pk_fma_f32 v[18:19], v[18:19], v[220:221], v[42:43]
	v_cvt_pk_bf16_f32 v36, v30, v31
	v_cvt_pk_bf16_f32 v37, v32, v33
	v_cvt_pk_bf16_f32 v38, v26, v27
	v_cvt_pk_bf16_f32 v39, v28, v29
	v_cvt_pk_bf16_f32 v40, v22, v23
	v_cvt_pk_bf16_f32 v41, v24, v25
	s_nop 0
	v_cvt_pk_bf16_f32 v42, v18, v19
	v_cvt_pk_bf16_f32 v43, v20, v21
	global_store_dwordx4 v[54:55], v[36:39], off
	global_store_dwordx4 v[54:55], v[40:43], off offset:64
	s_and_saveexec_b64 s[0:1], vcc
	s_cbranch_execz .LBB0_358
	v_lshl_add_u64 v[34:35], s[16:17], 2, v[34:35]
	v_lshlrev_b32_e32 v36, 2, v138
	v_mov_b32_e32 v37, v1
	v_lshl_add_u64 v[34:35], v[34:35], 0, v[36:37]
	global_store_dwordx4 v[34:35], v[30:33], off offset:-4096
	global_store_dwordx4 v[34:35], v[26:29], off offset:-4080
	global_store_dwordx4 v[34:35], v[22:25], off offset:-3968
	global_store_dwordx4 v[34:35], v[18:21], off offset:-3952

.LBB0_371:
	s_and_b64 vcc, exec, s[4:5]
	s_cbranch_vccz .LBB0_241
	v_and_b32_e32 v0, 0x7ff, v26
	v_cmp_gt_i32_e32 vcc, s94, v26
	v_lshl_add_u64 v[20:21], s[16:17], 1, v[20:21]
	v_mov_b32_e32 v159, v1
	v_cndmask_b32_e32 v0, v169, v0, vcc
	v_lshlrev_b32_e32 v0, 7, v0
	v_lshl_add_u64 v[26:27], v[142:143], 0, v[0:1]
	s_nop 0
	v_lshl_add_u64 v[34:35], v[140:141], 0, v[0:1]
	s_nop 0
	v_lshl_add_u64 v[38:39], v[20:21], 0, v[158:159]
	v_cmp_ne_u64_e32 vcc, 0, v[18:19]
	s_waitcnt vmcnt(2)
	v_pk_mul_f32 v[20:21], v[8:9], v[226:227]
	v_pk_mul_f32 v[40:41], v[6:7], v[224:225]
	v_pk_mul_f32 v[42:43], v[4:5], v[230:231]
	v_pk_mul_f32 v[44:45], v[2:3], v[228:229]
	v_pk_mul_f32 v[24:25], v[16:17], v[226:227]
	v_pk_mul_f32 v[22:23], v[14:15], v[224:225]
	v_pk_mul_f32 v[28:29], v[12:13], v[230:231]
	v_pk_mul_f32 v[26:27], v[10:11], v[228:229]
	v_pk_fma_f32 v[16:17], v[16:17], v[234:235], v[20:21] neg_lo:[0,0,1] neg_hi:[0,0,1]
	v_pk_fma_f32 v[14:15], v[14:15], v[232:233], v[40:41] neg_lo:[0,0,1] neg_hi:[0,0,1]
	v_pk_fma_f32 v[12:13], v[12:13], v[238:239], v[42:43] neg_lo:[0,0,1] neg_hi:[0,0,1]
	v_pk_fma_f32 v[10:11], v[10:11], v[236:237], v[44:45] neg_lo:[0,0,1] neg_hi:[0,0,1]
	v_pk_fma_f32 v[8:9], v[8:9], v[234:235], v[24:25]
	v_pk_fma_f32 v[6:7], v[6:7], v[232:233], v[22:23]
	v_pk_fma_f32 v[4:5], v[4:5], v[238:239], v[28:29]
	v_pk_fma_f32 v[2:3], v[2:3], v[236:237], v[26:27]
	v_cvt_pk_bf16_f32 v20, v14, v15
	v_cvt_pk_bf16_f32 v21, v16, v17
	v_cvt_pk_bf16_f32 v22, v10, v11
	v_cvt_pk_bf16_f32 v23, v12, v13
	v_cvt_pk_bf16_f32 v24, v6, v7
	v_cvt_pk_bf16_f32 v25, v8, v9
	s_nop 0
	v_cvt_pk_bf16_f32 v26, v2, v3
	v_cvt_pk_bf16_f32 v27, v4, v5
	global_store_dwordx4 v[38:39], v[20:23], off
	global_store_dwordx4 v[38:39], v[24:27], off offset:64
	s_and_saveexec_b64 s[0:1], vcc
	s_cbranch_execz .LBB0_240
	v_lshl_add_u64 v[18:19], s[16:17], 2, v[18:19]
	v_lshlrev_b32_e32 v0, 2, v138
	v_lshl_add_u64 v[18:19], v[18:19], 0, v[0:1]
	global_store_dwordx4 v[18:19], v[14:17], off offset:-4096
	global_store_dwordx4 v[18:19], v[10:13], off offset:-4080
	global_store_dwordx4 v[18:19], v[6:9], off offset:-3968
	global_store_dwordx4 v[18:19], v[2:5], off offset:-3952
	s_branch .LBB0_240
